# mem_tile prologue: 8 q-fragment loads issued together instead of load/wait x8
# baseline (speedup 1.0000x reference)
; __device__ __forceinline__ bf16x8 scale_q(u32x4 v, float s) { u32x4 w; w.x = cvt_pk_bf16(bf_lo(v.x) * s, bf_hi(v.x) * s); w.y = cvt_pk_bf16(bf_lo(v.y) * s, bf_hi(v.y) * s); w.z = cvt_pk_bf16(bf_lo(v.z) * s, bf_hi(v.z) * s); w.w = cvt_pk_bf16(bf_lo(v.w) * s, bf_hi(v.w) * s); return __builtin_bit_cast(bf16x8, w); }
; __device__ __forceinline__ void mem_tile(const Ctx& C, int b, int hm, int t0) {
;     ...
;     const float QS = 0.12751743082459868f;
;     bf16x8 q[8];
;     const bf16_t* qp = P + tok * PP + PC_QM + hm * 128;
; #pragma unroll
;     for (int s = 0; s < 8; ++s) q[s] = scale_q(*(const u32x4*)(qp + 16 * s + 8 * hi), QS);
;     const bf16x8* kb = (const bf16x8*)(C.ws + WS_MEMK) + (size_t)(b * 4 + hm) * 8 * 8 * 64 + lane;
;     const bf16x8* vb = (const bf16x8*)(C.ws + WS_MEMV) + (size_t)(b * 4 + hm) * 16 * 4 * 64 + lane;
;     float m = -1e30f, l = 0.f; f32x16 O[4];
; #pragma unroll
;     for (int i = 0; i < 16; ++i) { O[0][i] = 0.f; O[1][i] = 0.f; O[2][i] = 0.f; O[3][i] = 0.f; }
.LBB0_657:
	s_ashr_i32 s0, s5, 11
	s_lshl_b32 s1, s5, 5
	s_and_b32 s3, s1, 0x3fe0
	s_ashr_i32 s1, s0, 31
	s_lshl_b64 s[10:11], s[0:1], 14
	v_mov_b32_e32 v6, v252
	s_or_b32 s1, s10, s3
	v_mov_b64_e32 v[2:3], s[34:35]
	s_waitcnt vmcnt(12)
	v_and_or_b32 v146, v6, 31, s1
	s_bfe_u32 s4, s5, 0x20009
	v_ashrrev_i32_e32 v152, 5, v6
	v_mad_u64_u32 v[148:149], s[12:13], v146, s67, v[2:3]
	v_mad_i32_i24 v149, s11, v233, v149
	s_lshl_b32 s6, s4, 8
	v_lshlrev_b32_e32 v4, 3, v152
	v_lshl_add_u64 v[2:3], v[148:149], 0, s[6:7]
	v_ashrrev_i32_e32 v5, 31, v4
	v_mov_b32_e32 v147, s11
	v_lshl_add_u64 v[4:5], v[4:5], 1, v[2:3]
	s_mov_b64 s[10:11], 0x10201600
	s_mov_b32 s1, 0x10201000
	v_lshl_add_u64 v[2:3], v[4:5], 0, s[10:11]
	v_add_co_u32_e32 v4, vcc, s1, v4
	s_lshl_b32 s0, s0, 2
	s_nop 0
	v_addc_co_u32_e32 v5, vcc, 0, v5, vcc
	global_load_dwordx4 v[8:11], v[4:5], off offset:1536
	global_load_dwordx4 v[114:117], v[2:3], off offset:32
	global_load_dwordx4 v[118:121], v[2:3], off offset:64
	global_load_dwordx4 v[122:125], v[2:3], off offset:96
	global_load_dwordx4 v[126:129], v[2:3], off offset:128
	global_load_dwordx4 v[130:133], v[2:3], off offset:160
	global_load_dwordx4 v[134:137], v[2:3], off offset:192
	global_load_dwordx4 v[138:141], v[2:3], off offset:224
	s_or_b32 s0, s0, s4
	s_ashr_i32 s1, s0, 31
	s_lshl_b32 s3, s4, 7
	s_lshl_b64 s[0:1], s[0:1], 16
	s_add_u32 s0, s34, s0
	v_ashrrev_i32_e32 v7, 31, v6
	s_addc_u32 s1, s35, s1
	v_mov_b32_e32 v14, v1
	v_mov_b32_e32 v15, v1
	v_lshl_add_u64 v[150:151], v[6:7], 4, s[0:1]
	v_mov_b32_e32 v0, v1
	v_mov_b32_e32 v6, v1
	v_mov_b32_e32 v7, v1
	v_mov_b32_e32 v12, v1
	v_mov_b32_e32 v13, v1
	v_mov_b32_e32 v153, 0
	v_mov_b32_e32 v154, 0xf149f2ca
	s_mov_b64 s[0:1], 0
	s_waitcnt vmcnt(0)
	v_lshlrev_b32_e32 v4, 16, v8
	v_and_b32_e32 v5, 0xffff0000, v8
	v_pk_mul_f32 v[4:5], v[4:5], s[14:15] op_sel_hi:[1,0]
	s_nop 0
	v_cvt_pk_bf16_f32 v82, v4, v5
	v_lshlrev_b32_e32 v4, 16, v9
	v_and_b32_e32 v5, 0xffff0000, v9
	v_pk_mul_f32 v[4:5], v[4:5], s[14:15] op_sel_hi:[1,0]
	s_nop 0
	v_cvt_pk_bf16_f32 v83, v4, v5
	v_lshlrev_b32_e32 v4, 16, v10
	v_and_b32_e32 v5, 0xffff0000, v10
	v_pk_mul_f32 v[4:5], v[4:5], s[14:15] op_sel_hi:[1,0]
	s_nop 0
	v_cvt_pk_bf16_f32 v84, v4, v5
	v_lshlrev_b32_e32 v4, 16, v11
	v_and_b32_e32 v5, 0xffff0000, v11
	v_mov_b32_e32 v8, v114
	v_mov_b32_e32 v9, v115
	v_mov_b32_e32 v10, v116
	v_mov_b32_e32 v11, v117
	v_pk_mul_f32 v[4:5], v[4:5], s[14:15] op_sel_hi:[1,0]
	s_nop 0
	v_cvt_pk_bf16_f32 v85, v4, v5
	s_waitcnt vmcnt(0)
	v_lshlrev_b32_e32 v4, 16, v8
	v_and_b32_e32 v5, 0xffff0000, v8
	v_pk_mul_f32 v[4:5], v[4:5], s[14:15] op_sel_hi:[1,0]
	s_nop 0
	v_cvt_pk_bf16_f32 v86, v4, v5
	v_lshlrev_b32_e32 v4, 16, v9
	v_and_b32_e32 v5, 0xffff0000, v9
	v_pk_mul_f32 v[4:5], v[4:5], s[14:15] op_sel_hi:[1,0]
	s_nop 0
	v_cvt_pk_bf16_f32 v87, v4, v5
	v_lshlrev_b32_e32 v4, 16, v10
	v_and_b32_e32 v5, 0xffff0000, v10
	v_pk_mul_f32 v[4:5], v[4:5], s[14:15] op_sel_hi:[1,0]
	s_nop 0
	v_cvt_pk_bf16_f32 v88, v4, v5
	v_lshlrev_b32_e32 v4, 16, v11
	v_and_b32_e32 v5, 0xffff0000, v11
	v_mov_b32_e32 v8, v118
	v_mov_b32_e32 v9, v119
	v_mov_b32_e32 v10, v120
	v_mov_b32_e32 v11, v121
	v_pk_mul_f32 v[4:5], v[4:5], s[14:15] op_sel_hi:[1,0]
	s_nop 0
	v_cvt_pk_bf16_f32 v89, v4, v5
	s_waitcnt vmcnt(0)
	v_lshlrev_b32_e32 v4, 16, v8
	v_and_b32_e32 v5, 0xffff0000, v8
	v_pk_mul_f32 v[4:5], v[4:5], s[14:15] op_sel_hi:[1,0]
	s_nop 0
	v_cvt_pk_bf16_f32 v90, v4, v5
	v_lshlrev_b32_e32 v4, 16, v9
	v_and_b32_e32 v5, 0xffff0000, v9
	v_pk_mul_f32 v[4:5], v[4:5], s[14:15] op_sel_hi:[1,0]
	s_nop 0
	v_cvt_pk_bf16_f32 v91, v4, v5
	v_lshlrev_b32_e32 v4, 16, v10
	v_and_b32_e32 v5, 0xffff0000, v10
	v_pk_mul_f32 v[4:5], v[4:5], s[14:15] op_sel_hi:[1,0]
	s_nop 0
	v_cvt_pk_bf16_f32 v92, v4, v5
	v_lshlrev_b32_e32 v4, 16, v11
	v_and_b32_e32 v5, 0xffff0000, v11
	v_mov_b32_e32 v8, v122
	v_mov_b32_e32 v9, v123
	v_mov_b32_e32 v10, v124
	v_mov_b32_e32 v11, v125
	v_pk_mul_f32 v[4:5], v[4:5], s[14:15] op_sel_hi:[1,0]
	s_nop 0
	v_cvt_pk_bf16_f32 v93, v4, v5
	s_waitcnt vmcnt(0)
	v_lshlrev_b32_e32 v4, 16, v8
	v_and_b32_e32 v5, 0xffff0000, v8
	v_pk_mul_f32 v[4:5], v[4:5], s[14:15] op_sel_hi:[1,0]
	s_nop 0
	v_cvt_pk_bf16_f32 v94, v4, v5
	v_lshlrev_b32_e32 v4, 16, v9
	v_and_b32_e32 v5, 0xffff0000, v9
	v_pk_mul_f32 v[4:5], v[4:5], s[14:15] op_sel_hi:[1,0]
	s_nop 0
	v_cvt_pk_bf16_f32 v95, v4, v5
	v_lshlrev_b32_e32 v4, 16, v10
	v_and_b32_e32 v5, 0xffff0000, v10
	v_pk_mul_f32 v[4:5], v[4:5], s[14:15] op_sel_hi:[1,0]
	s_nop 0
	v_cvt_pk_bf16_f32 v96, v4, v5
	v_lshlrev_b32_e32 v4, 16, v11
	v_and_b32_e32 v5, 0xffff0000, v11
	v_mov_b32_e32 v8, v126
	v_mov_b32_e32 v9, v127
	v_mov_b32_e32 v10, v128
	v_mov_b32_e32 v11, v129
	v_pk_mul_f32 v[4:5], v[4:5], s[14:15] op_sel_hi:[1,0]
	s_nop 0
	v_cvt_pk_bf16_f32 v97, v4, v5
	s_waitcnt vmcnt(0)
; __device__ __forceinline__ bf16x8 scale_q(u32x4 v, float s) { u32x4 w; w.x = cvt_pk_bf16(bf_lo(v.x) * s, bf_hi(v.x) * s); w.y = cvt_pk_bf16(bf_lo(v.y) * s, bf_hi(v.y) * s); w.z = cvt_pk_bf16(bf_lo(v.z) * s, bf_hi(v.z) * s); w.w = cvt_pk_bf16(bf_lo(v.w) * s, bf_hi(v.w) * s); return __builtin_bit_cast(bf16x8, w); }
; __device__ __forceinline__ void mem_tile(const Ctx& C, int b, int hm, int t0) {
;     ...
;     bf16x8 q[8];
;     const bf16_t* qp = P + tok * PP + PC_QM + hm * 128;
; #pragma unroll
;     for (int s = 0; s < 8; ++s) q[s] = scale_q(*(const u32x4*)(qp + 16 * s + 8 * hi), QS);
;     const bf16x8* kb = (const bf16x8*)(C.ws + WS_MEMK) + (size_t)(b * 4 + hm) * 8 * 8 * 64 + lane;
;     const bf16x8* vb = (const bf16x8*)(C.ws + WS_MEMV) + (size_t)(b * 4 + hm) * 16 * 4 * 64 + lane;
;     float m = -1e30f, l = 0.f; f32x16 O[4];
; #pragma unroll
;     for (int i = 0; i < 16; ++i) { O[0][i] = 0.f; O[1][i] = 0.f; O[2][i] = 0.f; O[3][i] = 0.f; }
	v_lshlrev_b32_e32 v4, 16, v8
	v_and_b32_e32 v5, 0xffff0000, v8
	v_pk_mul_f32 v[4:5], v[4:5], s[14:15] op_sel_hi:[1,0]
	s_nop 0
	v_cvt_pk_bf16_f32 v98, v4, v5
	v_lshlrev_b32_e32 v4, 16, v9
	v_and_b32_e32 v5, 0xffff0000, v9
	v_pk_mul_f32 v[4:5], v[4:5], s[14:15] op_sel_hi:[1,0]
	s_nop 0
	v_cvt_pk_bf16_f32 v99, v4, v5
	v_lshlrev_b32_e32 v4, 16, v10
	v_and_b32_e32 v5, 0xffff0000, v10
	v_pk_mul_f32 v[4:5], v[4:5], s[14:15] op_sel_hi:[1,0]
	s_nop 0
	v_cvt_pk_bf16_f32 v100, v4, v5
	v_lshlrev_b32_e32 v4, 16, v11
	v_and_b32_e32 v5, 0xffff0000, v11
	v_mov_b32_e32 v8, v130
	v_mov_b32_e32 v9, v131
	v_mov_b32_e32 v10, v132
	v_mov_b32_e32 v11, v133
	v_pk_mul_f32 v[4:5], v[4:5], s[14:15] op_sel_hi:[1,0]
	s_nop 0
	v_cvt_pk_bf16_f32 v101, v4, v5
	s_waitcnt vmcnt(0)
	v_lshlrev_b32_e32 v4, 16, v8
	v_and_b32_e32 v5, 0xffff0000, v8
	v_pk_mul_f32 v[4:5], v[4:5], s[14:15] op_sel_hi:[1,0]
	s_nop 0
	v_cvt_pk_bf16_f32 v102, v4, v5
	v_lshlrev_b32_e32 v4, 16, v9
	v_and_b32_e32 v5, 0xffff0000, v9
	v_pk_mul_f32 v[4:5], v[4:5], s[14:15] op_sel_hi:[1,0]
	s_nop 0
	v_cvt_pk_bf16_f32 v103, v4, v5
	v_lshlrev_b32_e32 v4, 16, v10
	v_and_b32_e32 v5, 0xffff0000, v10
	v_pk_mul_f32 v[4:5], v[4:5], s[14:15] op_sel_hi:[1,0]
	s_nop 0
	v_cvt_pk_bf16_f32 v104, v4, v5
	v_lshlrev_b32_e32 v4, 16, v11
	v_and_b32_e32 v5, 0xffff0000, v11
	v_mov_b32_e32 v8, v134
	v_mov_b32_e32 v9, v135
	v_mov_b32_e32 v10, v136
	v_mov_b32_e32 v11, v137
	v_pk_mul_f32 v[4:5], v[4:5], s[14:15] op_sel_hi:[1,0]
	s_nop 0
	v_cvt_pk_bf16_f32 v105, v4, v5
	s_waitcnt vmcnt(0)
	v_lshlrev_b32_e32 v4, 16, v8
	v_and_b32_e32 v5, 0xffff0000, v8
	v_pk_mul_f32 v[4:5], v[4:5], s[14:15] op_sel_hi:[1,0]
	s_nop 0
	v_cvt_pk_bf16_f32 v106, v4, v5
	v_lshlrev_b32_e32 v4, 16, v9
	v_and_b32_e32 v5, 0xffff0000, v9
	v_pk_mul_f32 v[4:5], v[4:5], s[14:15] op_sel_hi:[1,0]
	s_nop 0
	v_cvt_pk_bf16_f32 v107, v4, v5
	v_lshlrev_b32_e32 v4, 16, v10
	v_and_b32_e32 v5, 0xffff0000, v10
	v_pk_mul_f32 v[4:5], v[4:5], s[14:15] op_sel_hi:[1,0]
	v_mov_b32_e32 v10, v1
	v_cvt_pk_bf16_f32 v108, v4, v5
	v_lshlrev_b32_e32 v4, 16, v11
	v_and_b32_e32 v5, 0xffff0000, v11
	v_pk_mul_f32 v[4:5], v[4:5], s[14:15] op_sel_hi:[1,0]
	v_mov_b32_e32 v11, v1
	v_cvt_pk_bf16_f32 v109, v4, v5
	v_mov_b32_e32 v2, v138
	v_mov_b32_e32 v3, v139
	v_mov_b32_e32 v4, v140
	v_mov_b32_e32 v5, v141
	s_waitcnt vmcnt(0)
	v_lshlrev_b32_e32 v8, 16, v2
	v_and_b32_e32 v9, 0xffff0000, v2
	v_lshlrev_b32_e32 v2, 16, v3
	v_and_b32_e32 v3, 0xffff0000, v3
	v_pk_mul_f32 v[2:3], v[2:3], s[14:15] op_sel_hi:[1,0]
	v_pk_mul_f32 v[8:9], v[8:9], s[14:15] op_sel_hi:[1,0]
	v_cvt_pk_bf16_f32 v111, v2, v3
	v_lshlrev_b32_e32 v2, 16, v4
	v_and_b32_e32 v3, 0xffff0000, v4
	v_pk_mul_f32 v[2:3], v[2:3], s[14:15] op_sel_hi:[1,0]
	v_cvt_pk_bf16_f32 v110, v8, v9
	v_cvt_pk_bf16_f32 v112, v2, v3
	v_lshlrev_b32_e32 v2, 16, v5
	v_and_b32_e32 v3, 0xffff0000, v5
	v_pk_mul_f32 v[2:3], v[2:3], s[14:15] op_sel_hi:[1,0]
	v_mov_b32_e32 v4, v1
	v_cvt_pk_bf16_f32 v113, v2, v3
	v_mov_b32_e32 v2, v1
	v_mov_b32_e32 v3, v1
	v_mov_b32_e32 v5, v1
	v_mov_b32_e32 v8, v1
	v_mov_b32_e32 v9, v1
	v_mov_b64_e32 v[64:65], v[14:15]
	v_mov_b64_e32 v[48:49], v[14:15]
	v_mov_b64_e32 v[32:33], v[14:15]
	v_mov_b64_e32 v[62:63], v[12:13]
	v_mov_b64_e32 v[60:61], v[10:11]
	v_mov_b64_e32 v[58:59], v[8:9]
	v_mov_b64_e32 v[56:57], v[6:7]
	v_mov_b64_e32 v[54:55], v[4:5]
	v_mov_b64_e32 v[52:53], v[2:3]
	v_mov_b64_e32 v[50:51], v[0:1]
	v_mov_b64_e32 v[46:47], v[12:13]
	v_mov_b64_e32 v[44:45], v[10:11]
	v_mov_b64_e32 v[42:43], v[8:9]
	v_mov_b64_e32 v[40:41], v[6:7]
	v_mov_b64_e32 v[38:39], v[4:5]
	v_mov_b64_e32 v[36:37], v[2:3]
	v_mov_b64_e32 v[34:35], v[0:1]
	v_mov_b64_e32 v[30:31], v[12:13]
	v_mov_b64_e32 v[28:29], v[10:11]
	v_mov_b64_e32 v[26:27], v[8:9]
	v_mov_b64_e32 v[24:25], v[6:7]
	v_mov_b64_e32 v[22:23], v[4:5]
	v_mov_b64_e32 v[20:21], v[2:3]
	v_mov_b64_e32 v[18:19], v[0:1]
	v_mov_b64_e32 v[16:17], v[14:15]
	v_mov_b64_e32 v[14:15], v[12:13]
	v_mov_b64_e32 v[12:13], v[10:11]
	v_mov_b64_e32 v[10:11], v[8:9]
	v_mov_b64_e32 v[8:9], v[6:7]
	v_mov_b64_e32 v[6:7], v[4:5]
	v_mov_b64_e32 v[4:5], v[2:3]
	v_mov_b64_e32 v[2:3], v[0:1]
	s_branch .LBB0_659
